# attention loop: L2 prefetch of K/V tile t+4 by narrow loads two steps ahead, staging waits counted past the prefetches (on top of the relocated vmcnt wait)
# baseline (speedup 1.0000x reference)
.LBB0_1079:
	s_or_b64 exec, exec, s[28:29]
	s_lshr_b32 s30, s12, 1
	s_sub_i32 s31, 63, s30
	s_lshl_b32 s45, s31, 7
	s_lshl_b32 s12, s12, 7
	s_lshl_b32 s44, s34, 22
	v_or_b32_e32 v0, s45, v229
	s_and_b32 s28, s44, 0x800000
	s_and_b32 s12, s12, 0x80
	v_lshlrev_b32_e32 v0, 9, v0
	s_or_b32 s12, s28, s12
	v_lshl_add_u64 v[2:3], s[60:61], 0, v[0:1]
	s_lshl_b32 s12, s12, 1
	v_lshl_add_u64 v[2:3], v[2:3], 0, s[12:13]
	v_lshl_add_u64 v[2:3], s[18:19], 1, v[2:3]
	v_lshl_add_u64 v[2:3], v[182:183], 1, v[2:3]
	s_mov_b64 s[28:29], 0xe000000
	v_lshl_add_u64 v[4:5], v[2:3], 0, s[28:29]
	s_mov_b32 s28, 0xe000000
	v_add_co_u32_e32 v2, vcc, s28, v2
	v_lshl_add_u64 v[6:7], v[186:187], 0, s[12:13]
	s_nop 0
	v_addc_co_u32_e32 v3, vcc, 0, v3, vcc
	v_lshl_add_u64 v[26:27], v[180:181], 1, v[6:7]
	v_add_co_u32_e32 v6, vcc, s4, v26
	global_load_dwordx4 v[132:135], v[4:5], off offset:32
	global_load_dwordx4 v[136:139], v[4:5], off offset:64
	global_load_dwordx4 v[140:143], v[2:3], off
	global_load_dwordx4 v[144:147], v[4:5], off offset:96
	v_addc_co_u32_e32 v7, vcc, 0, v27, vcc
	v_add_co_u32_e32 v8, vcc, s5, v26
	s_mov_b64 s[28:29], 0x10000000
	s_nop 0
	v_addc_co_u32_e32 v9, vcc, 0, v27, vcc
	global_load_dwordx4 v[10:13], v[6:7], off
	global_load_dwordx4 v[14:17], v[8:9], off
	v_add_co_u32_e32 v6, vcc, s25, v26
	v_lshl_add_u64 v[190:191], v[26:27], 0, s[28:29]
	s_nop 0
	v_addc_co_u32_e32 v7, vcc, 0, v27, vcc
	v_add_co_u32_e32 v8, vcc, s33, v26
	s_mov_b64 s[28:29], 0x12000000
	s_nop 0
	v_addc_co_u32_e32 v9, vcc, 0, v27, vcc
	global_load_dwordx4 v[18:21], v[6:7], off
	global_load_dwordx4 v[22:25], v[8:9], off
	v_add_co_u32_e32 v6, vcc, s36, v26
	v_mov_b32_e32 v0, v1
	s_nop 0
	v_addc_co_u32_e32 v7, vcc, 0, v27, vcc
	v_add_co_u32_e32 v8, vcc, s37, v26
	v_lshl_add_u64 v[192:193], v[26:27], 0, s[28:29]
	s_nop 0
	v_addc_co_u32_e32 v9, vcc, 0, v27, vcc
	global_load_dwordx4 v[148:151], v[6:7], off
	global_load_dwordx4 v[152:155], v[8:9], off
	v_add_co_u32_e32 v6, vcc, s38, v26
	s_lshl_b32 s12, s30, 7
	s_nop 0
	v_addc_co_u32_e32 v7, vcc, 0, v27, vcc
	v_add_co_u32_e32 v8, vcc, s39, v26
	s_lshl_b32 s46, s31, 1
	s_nop 0
	v_addc_co_u32_e32 v9, vcc, 0, v27, vcc
	global_load_dwordx4 v[156:159], v[6:7], off
	global_load_dwordx4 v[160:163], v[8:9], off
	s_mov_b32 s100, 0x18000
	s_mov_b32 s101, 0
	v_lshl_add_u64 v[248:249], v[190:191], 0, s[100:101]
	global_load_dword v244, v[248:249], off
	v_lshl_add_u64 v[248:249], v[192:193], 0, s[100:101]
	global_load_dword v246, v[248:249], off
	s_mov_b32 s100, 0x1c000
	s_mov_b32 s101, 0
	v_lshl_add_u64 v[248:249], v[190:191], 0, s[100:101]
	global_load_dword v245, v[248:249], off
	v_lshl_add_u64 v[248:249], v[192:193], 0, s[100:101]
	global_load_dword v247, v[248:249], off
	v_mov_b32_e32 v2, v1
	v_mov_b32_e32 v3, v1
	v_mov_b32_e32 v4, v1
	v_mov_b32_e32 v5, v1
	v_mov_b32_e32 v6, v1
	v_mov_b32_e32 v7, v1
	v_mov_b32_e32 v8, v1
	v_mov_b32_e32 v9, v1
	v_subrev_u32_e32 v67, s12, v239
	s_add_i32 s47, s46, 2
	s_add_i32 s50, s46, -2
	v_mov_b32_e32 v242, 0
	v_mov_b32_e32 v66, 0xf149f2ca
	s_movk_i32 s28, 0xe0
	s_mov_b32 s51, 3
	s_waitcnt vmcnt(11)
	ds_write_b128 v226, v[10:13]
	s_waitcnt vmcnt(10)
	ds_write_b128 v227, v[14:17]
	s_waitcnt vmcnt(9)
	ds_write_b128 v232, v[18:21] offset:17408
	s_waitcnt vmcnt(8)
	ds_write_b128 v233, v[22:25] offset:17408
	v_mov_b32_e32 v14, v1
	v_mov_b32_e32 v15, v1
	s_waitcnt lgkmcnt(0)
	s_barrier
	v_mov_b32_e32 v10, v1
	v_mov_b32_e32 v11, v1
	v_mov_b32_e32 v12, v1
	v_mov_b32_e32 v13, v1
	v_mov_b64_e32 v[64:65], v[14:15]
	v_mov_b64_e32 v[48:49], v[14:15]
	v_mov_b64_e32 v[32:33], v[14:15]
	v_mov_b64_e32 v[62:63], v[12:13]
	v_mov_b64_e32 v[60:61], v[10:11]
	v_mov_b64_e32 v[58:59], v[8:9]
	v_mov_b64_e32 v[56:57], v[6:7]
	v_mov_b64_e32 v[54:55], v[4:5]
	v_mov_b64_e32 v[52:53], v[2:3]
	v_mov_b64_e32 v[50:51], v[0:1]
	v_mov_b64_e32 v[46:47], v[12:13]
	v_mov_b64_e32 v[44:45], v[10:11]
	v_mov_b64_e32 v[42:43], v[8:9]
	v_mov_b64_e32 v[40:41], v[6:7]
	v_mov_b64_e32 v[38:39], v[4:5]
	v_mov_b64_e32 v[36:37], v[2:3]
	v_mov_b64_e32 v[34:35], v[0:1]
	v_mov_b64_e32 v[30:31], v[12:13]
	v_mov_b64_e32 v[28:29], v[10:11]
	v_mov_b64_e32 v[26:27], v[8:9]
	v_mov_b64_e32 v[24:25], v[6:7]
	v_mov_b64_e32 v[22:23], v[4:5]
	v_mov_b64_e32 v[20:21], v[2:3]
	v_mov_b64_e32 v[18:19], v[0:1]
	v_mov_b64_e32 v[16:17], v[14:15]
	v_mov_b64_e32 v[14:15], v[12:13]
	v_mov_b64_e32 v[12:13], v[10:11]
	v_mov_b64_e32 v[10:11], v[8:9]
	v_mov_b64_e32 v[8:9], v[6:7]
	v_mov_b64_e32 v[6:7], v[4:5]
	v_mov_b64_e32 v[4:5], v[2:3]
	v_mov_b64_e32 v[2:3], v[0:1]
	s_branch .LBB0_1082

.LBB0_1082:
	s_add_i32 s52, s51, -3
	s_cmp_lt_u32 s52, s46
	s_cselect_b64 s[30:31], -1, 0
	s_cmp_ge_u32 s52, s46
	s_waitcnt vmcnt(7)
	ds_write_b128 v226, v[148:151] offset:37888
	s_waitcnt vmcnt(6)
	ds_write_b128 v227, v[152:155] offset:37888
	s_waitcnt vmcnt(5)
	ds_write_b128 v232, v[156:159] offset:55296
	s_waitcnt vmcnt(4)
	ds_write_b128 v233, v[160:163] offset:55296
	s_cbranch_scc1 .LBB0_1084
	s_add_i32 s12, s28, 0xffffffa0
	s_lshl_b64 s[34:35], s[12:13], 9
	s_sub_i32 s12, s28, 64
	v_lshl_add_u64 v[68:69], v[190:191], 0, s[34:35]
	s_lshl_b64 s[54:55], s[12:13], 9
	v_lshl_add_u64 v[70:71], v[190:191], 0, s[54:55]
	global_load_dwordx4 v[148:151], v[68:69], off
	global_load_dwordx4 v[152:155], v[70:71], off
	v_lshl_add_u64 v[68:69], v[192:193], 0, s[34:35]
	v_lshl_add_u64 v[70:71], v[192:193], 0, s[54:55]
	global_load_dwordx4 v[156:159], v[68:69], off
	global_load_dwordx4 v[160:163], v[70:71], off
	s_add_u32 s100, s34, 0x10000
	s_addc_u32 s101, s35, 0
	v_lshl_add_u64 v[248:249], v[190:191], 0, s[100:101]
	global_load_dword v244, v[248:249], off
	v_lshl_add_u64 v[248:249], v[192:193], 0, s[100:101]
	global_load_dword v246, v[248:249], off
	s_add_u32 s100, s54, 0x10000
	s_addc_u32 s101, s55, 0
	v_lshl_add_u64 v[248:249], v[190:191], 0, s[100:101]
	global_load_dword v245, v[248:249], off
	v_lshl_add_u64 v[248:249], v[192:193], 0, s[100:101]
	global_load_dword v247, v[248:249], off

.LBB0_1152:
	v_sub_f32_e32 v0, v91, v66
	v_sub_f32_e32 v90, v90, v66
	v_sub_f32_e32 v89, v89, v66
	v_sub_f32_e32 v88, v88, v66
	v_sub_f32_e32 v87, v87, v66
	v_sub_f32_e32 v86, v86, v66
	v_sub_f32_e32 v85, v85, v66
	v_sub_f32_e32 v84, v84, v66
	v_exp_f32_e32 v196, v84
	v_exp_f32_e32 v197, v85
	v_exp_f32_e32 v200, v86
	v_exp_f32_e32 v201, v87
	v_exp_f32_e32 v198, v88
	v_exp_f32_e32 v199, v89
	v_exp_f32_e32 v194, v90
	v_exp_f32_e32 v195, v0
	v_cvt_pk_bf16_f32 v84, v196, v197
	v_cvt_pk_bf16_f32 v85, v200, v201
	v_cvt_pk_bf16_f32 v86, v198, v199
	v_cvt_pk_bf16_f32 v87, v194, v195
	v_sub_f32_e32 v0, v99, v66
	v_sub_f32_e32 v88, v98, v66
	s_waitcnt lgkmcnt(3)
	v_mfma_f32_32x32x16_bf16 v[50:65], v[176:179], v[84:87], v[50:65]
	v_sub_f32_e32 v89, v97, v66
	v_sub_f32_e32 v90, v96, v66
	v_sub_f32_e32 v91, v95, v66
	v_sub_f32_e32 v94, v94, v66
	v_sub_f32_e32 v93, v93, v66
	v_sub_f32_e32 v92, v92, v66
	v_exp_f32_e32 v204, v92
	s_waitcnt lgkmcnt(2)
	v_mfma_f32_32x32x16_bf16 v[34:49], v[172:175], v[84:87], v[34:49]
	v_exp_f32_e32 v205, v93
	v_exp_f32_e32 v208, v94
	v_exp_f32_e32 v209, v91
	v_exp_f32_e32 v202, v90
	v_exp_f32_e32 v203, v89
	v_exp_f32_e32 v206, v88
	v_exp_f32_e32 v207, v0
	s_waitcnt lgkmcnt(1)
	v_mfma_f32_32x32x16_bf16 v[18:33], v[168:171], v[84:87], v[18:33]
	ds_read_b64_tr_b16 v[92:93], v235 offset:22528
	ds_read_b64_tr_b16 v[94:95], v235 offset:25088
	v_cvt_pk_bf16_f32 v88, v204, v205
	v_cvt_pk_bf16_f32 v89, v208, v209
	v_cvt_pk_bf16_f32 v90, v202, v203
	v_cvt_pk_bf16_f32 v91, v206, v207
	v_sub_f32_e32 v0, v75, v66
	v_sub_f32_e32 v74, v74, v66
	s_waitcnt lgkmcnt(2)
	v_mfma_f32_32x32x16_bf16 v[2:17], v[164:167], v[84:87], v[2:17]
	ds_read_b64_tr_b16 v[84:85], v235 offset:22592
	ds_read_b64_tr_b16 v[96:97], v235 offset:22656
	ds_read_b64_tr_b16 v[100:101], v235 offset:22720
	ds_read_b64_tr_b16 v[86:87], v235 offset:25152
	ds_read_b64_tr_b16 v[98:99], v235 offset:25216
	ds_read_b64_tr_b16 v[102:103], v235 offset:25280
	v_sub_f32_e32 v73, v73, v66
	v_sub_f32_e32 v72, v72, v66
	v_sub_f32_e32 v71, v71, v66
	v_sub_f32_e32 v70, v70, v66
	v_sub_f32_e32 v69, v69, v66
	v_sub_f32_e32 v68, v68, v66
	s_waitcnt lgkmcnt(6)
	v_mfma_f32_32x32x16_bf16 v[50:65], v[92:95], v[88:91], v[50:65]
	v_exp_f32_e32 v214, v68
	v_exp_f32_e32 v215, v69
	v_exp_f32_e32 v216, v70
	v_exp_f32_e32 v217, v71
	v_exp_f32_e32 v210, v72
	v_exp_f32_e32 v211, v73
	v_exp_f32_e32 v212, v74
	s_waitcnt lgkmcnt(2)
	v_mfma_f32_32x32x16_bf16 v[34:49], v[84:87], v[88:91], v[34:49]
	v_exp_f32_e32 v213, v0
	ds_read_b64_tr_b16 v[72:73], v235 offset:27648
	ds_read_b64_tr_b16 v[74:75], v235 offset:30208
	v_cvt_pk_bf16_f32 v68, v214, v215
	v_cvt_pk_bf16_f32 v69, v216, v217
	v_cvt_pk_bf16_f32 v70, v210, v211
	v_cvt_pk_bf16_f32 v71, v212, v213
	v_sub_f32_e32 v0, v83, v66
	s_waitcnt lgkmcnt(3)
	v_mfma_f32_32x32x16_bf16 v[18:33], v[96:99], v[88:91], v[18:33]
	v_sub_f32_e32 v78, v78, v66
	v_sub_f32_e32 v77, v77, v66
	v_sub_f32_e32 v76, v76, v66
	v_exp_f32_e32 v222, v76
	v_exp_f32_e32 v223, v77
	v_exp_f32_e32 v224, v78
	v_exp_f32_e32 v221, v0
	s_waitcnt lgkmcnt(2)
	v_mfma_f32_32x32x16_bf16 v[2:17], v[100:103], v[88:91], v[2:17]
	ds_read_b64_tr_b16 v[84:85], v235 offset:27712
	ds_read_b64_tr_b16 v[88:89], v235 offset:27776
	ds_read_b64_tr_b16 v[92:93], v235 offset:27840
	ds_read_b64_tr_b16 v[86:87], v235 offset:30272
	ds_read_b64_tr_b16 v[90:91], v235 offset:30336
	ds_read_b64_tr_b16 v[94:95], v235 offset:30400
	s_andn2_b64 vcc, exec, s[30:31]
	s_waitcnt lgkmcnt(6)
	v_mfma_f32_32x32x16_bf16 v[50:65], v[72:75], v[68:71], v[50:65]
	v_sub_f32_e32 v72, v82, v66
	v_sub_f32_e32 v73, v81, v66
	v_sub_f32_e32 v74, v80, v66
	v_sub_f32_e32 v75, v79, v66
	v_exp_f32_e32 v225, v75
	v_exp_f32_e32 v218, v74
	v_exp_f32_e32 v219, v73
	s_waitcnt lgkmcnt(2)
	v_mfma_f32_32x32x16_bf16 v[34:49], v[84:87], v[68:71], v[34:49]
	v_exp_f32_e32 v220, v72
	ds_read_b64_tr_b16 v[76:77], v235 offset:32768
	ds_read_b64_tr_b16 v[78:79], v235 offset:35328
	v_cvt_pk_bf16_f32 v72, v222, v223
	v_cvt_pk_bf16_f32 v73, v224, v225
	v_cvt_pk_bf16_f32 v74, v218, v219
	v_cvt_pk_bf16_f32 v75, v220, v221
	s_waitcnt lgkmcnt(3)
	v_mfma_f32_32x32x16_bf16 v[18:33], v[88:91], v[68:71], v[18:33]
	s_waitcnt lgkmcnt(2)
	v_mfma_f32_32x32x16_bf16 v[2:17], v[92:95], v[68:71], v[2:17]
	ds_read_b64_tr_b16 v[68:69], v235 offset:32832
	ds_read_b64_tr_b16 v[80:81], v235 offset:32896
	ds_read_b64_tr_b16 v[84:85], v235 offset:32960
	ds_read_b64_tr_b16 v[70:71], v235 offset:35392
	ds_read_b64_tr_b16 v[82:83], v235 offset:35456
	ds_read_b64_tr_b16 v[86:87], v235 offset:35520
	s_waitcnt lgkmcnt(0)
	s_barrier
	s_waitcnt lgkmcnt(6)
	v_mfma_f32_32x32x16_bf16 v[50:65], v[76:79], v[72:75], v[50:65]
	s_waitcnt lgkmcnt(2)
	v_mfma_f32_32x32x16_bf16 v[34:49], v[68:71], v[72:75], v[34:49]
	s_waitcnt lgkmcnt(1)
	v_mfma_f32_32x32x16_bf16 v[18:33], v[80:83], v[72:75], v[18:33]
	s_waitcnt lgkmcnt(0)
	v_mfma_f32_32x32x16_bf16 v[2:17], v[84:87], v[72:75], v[2:17]
	s_cbranch_vccnz .LBB0_1154
	s_waitcnt vmcnt(7)
	ds_write_b128 v226, v[148:151]
	s_waitcnt vmcnt(6)
	ds_write_b128 v227, v[152:155]
	s_waitcnt vmcnt(5)
	ds_write_b128 v232, v[156:159] offset:17408
	s_waitcnt vmcnt(4)
	ds_write_b128 v233, v[160:163] offset:17408
.LBB0_1154:
	s_cmp_ge_u32 s51, s47
	s_cbranch_scc1 .LBB0_1156
	s_sub_i32 s12, s28, 32
	s_lshl_b64 s[30:31], s[12:13], 9
	s_mov_b32 s29, s13
	v_lshl_add_u64 v[68:69], v[190:191], 0, s[30:31]
	s_lshl_b64 s[34:35], s[28:29], 9
	v_lshl_add_u64 v[70:71], v[190:191], 0, s[34:35]
	global_load_dwordx4 v[148:151], v[68:69], off
	global_load_dwordx4 v[152:155], v[70:71], off
	v_lshl_add_u64 v[68:69], v[192:193], 0, s[30:31]
	v_lshl_add_u64 v[70:71], v[192:193], 0, s[34:35]
	global_load_dwordx4 v[156:159], v[68:69], off
	global_load_dwordx4 v[160:163], v[70:71], off
	s_add_u32 s100, s30, 0x10000
	s_addc_u32 s101, s31, 0
	v_lshl_add_u64 v[248:249], v[190:191], 0, s[100:101]
	global_load_dword v244, v[248:249], off
	v_lshl_add_u64 v[248:249], v[192:193], 0, s[100:101]
	global_load_dword v246, v[248:249], off
	s_add_u32 s100, s34, 0x10000
	s_addc_u32 s101, s35, 0
	v_lshl_add_u64 v[248:249], v[190:191], 0, s[100:101]
	global_load_dword v245, v[248:249], off
	v_lshl_add_u64 v[248:249], v[192:193], 0, s[100:101]
	global_load_dword v247, v[248:249], off

.LBB0_2339:
	s_or_b64 exec, exec, s[36:37]
	s_lshr_b32 s36, s12, 1
	s_sub_i32 s37, 63, s36
	s_lshl_b32 s55, s37, 7
	s_lshl_b32 s12, s12, 7
	s_lshl_b32 s54, s40, 22
	v_or_b32_e32 v0, s55, v230
	s_and_b32 s38, s54, 0x800000
	s_and_b32 s12, s12, 0x80
	v_lshlrev_b32_e32 v0, 9, v0
	s_or_b32 s12, s38, s12
	v_lshl_add_u64 v[2:3], s[60:61], 0, v[0:1]
	s_lshl_b32 s12, s12, 1
	v_lshl_add_u64 v[2:3], v[2:3], 0, s[12:13]
	v_lshl_add_u64 v[2:3], s[18:19], 1, v[2:3]
	v_lshl_add_u64 v[2:3], v[182:183], 1, v[2:3]
	v_lshl_add_u64 v[4:5], v[2:3], 0, s[24:25]
	v_add_co_u32_e32 v2, vcc, s5, v2
	v_lshl_add_u64 v[6:7], v[186:187], 0, s[12:13]
	s_nop 0
	v_addc_co_u32_e32 v3, vcc, 0, v3, vcc
	v_lshl_add_u64 v[26:27], v[180:181], 1, v[6:7]
	v_add_co_u32_e32 v6, vcc, s31, v26
	global_load_dwordx4 v[132:135], v[4:5], off offset:32
	global_load_dwordx4 v[136:139], v[4:5], off offset:64
	global_load_dwordx4 v[140:143], v[2:3], off
	global_load_dwordx4 v[144:147], v[4:5], off offset:96
	v_addc_co_u32_e32 v7, vcc, 0, v27, vcc
	v_add_co_u32_e32 v8, vcc, s33, v26
	v_mov_b32_e32 v0, v1
	s_nop 0
	v_addc_co_u32_e32 v9, vcc, 0, v27, vcc
	global_load_dwordx4 v[10:13], v[6:7], off
	global_load_dwordx4 v[14:17], v[8:9], off
	v_add_co_u32_e32 v6, vcc, s42, v26
	v_lshl_add_u64 v[190:191], v[26:27], 0, s[26:27]
	s_nop 0
	v_addc_co_u32_e32 v7, vcc, 0, v27, vcc
	v_add_co_u32_e32 v8, vcc, s43, v26
	v_lshl_add_u64 v[192:193], v[26:27], 0, s[28:29]
	s_nop 0
	v_addc_co_u32_e32 v9, vcc, 0, v27, vcc
	global_load_dwordx4 v[18:21], v[6:7], off
	global_load_dwordx4 v[22:25], v[8:9], off
	v_add_co_u32_e32 v6, vcc, s44, v26
	s_lshl_b32 s12, s36, 7
	s_nop 0
	v_addc_co_u32_e32 v7, vcc, 0, v27, vcc
	v_add_co_u32_e32 v8, vcc, s45, v26
	s_lshl_b32 s56, s37, 1
	s_nop 0
	v_addc_co_u32_e32 v9, vcc, 0, v27, vcc
	global_load_dwordx4 v[148:151], v[6:7], off
	global_load_dwordx4 v[152:155], v[8:9], off
	v_add_co_u32_e32 v6, vcc, s46, v26
	v_subrev_u32_e32 v67, s12, v239
	s_nop 0
	v_addc_co_u32_e32 v7, vcc, 0, v27, vcc
	v_add_co_u32_e32 v8, vcc, s47, v26
	s_add_i32 s66, s56, 2
	s_nop 0
	v_addc_co_u32_e32 v9, vcc, 0, v27, vcc
	global_load_dwordx4 v[156:159], v[6:7], off
	global_load_dwordx4 v[160:163], v[8:9], off
	s_mov_b32 s100, 0x18000
	s_mov_b32 s101, 0
	v_lshl_add_u64 v[248:249], v[190:191], 0, s[100:101]
	global_load_dword v244, v[248:249], off
	v_lshl_add_u64 v[248:249], v[192:193], 0, s[100:101]
	global_load_dword v246, v[248:249], off
	s_mov_b32 s100, 0x1c000
	s_mov_b32 s101, 0
	v_lshl_add_u64 v[248:249], v[190:191], 0, s[100:101]
	global_load_dword v245, v[248:249], off
	v_lshl_add_u64 v[248:249], v[192:193], 0, s[100:101]
	global_load_dword v247, v[248:249], off
	v_mov_b32_e32 v2, v1
	v_mov_b32_e32 v3, v1
	v_mov_b32_e32 v4, v1
	v_mov_b32_e32 v5, v1
	v_mov_b32_e32 v6, v1
	v_mov_b32_e32 v7, v1
	v_mov_b32_e32 v8, v1
	v_mov_b32_e32 v9, v1
	s_add_i32 s67, s56, -2
	v_mov_b32_e32 v242, 0
	v_mov_b32_e32 v66, 0xf149f2ca
	s_movk_i32 s36, 0xe0
	s_mov_b32 s68, 3
	s_waitcnt vmcnt(11)
	ds_write_b128 v227, v[10:13]
	s_waitcnt vmcnt(10)
	ds_write_b128 v228, v[14:17]
	s_waitcnt vmcnt(9)
	ds_write_b128 v232, v[18:21] offset:17408
	s_waitcnt vmcnt(8)
	ds_write_b128 v233, v[22:25] offset:17408
	v_mov_b32_e32 v14, v1
	v_mov_b32_e32 v15, v1
	s_waitcnt lgkmcnt(0)
	s_barrier
	v_mov_b32_e32 v10, v1
	v_mov_b32_e32 v11, v1
	v_mov_b32_e32 v12, v1
	v_mov_b32_e32 v13, v1
	v_mov_b64_e32 v[64:65], v[14:15]
	v_mov_b64_e32 v[48:49], v[14:15]
	v_mov_b64_e32 v[32:33], v[14:15]
	v_mov_b64_e32 v[62:63], v[12:13]
	v_mov_b64_e32 v[60:61], v[10:11]
	v_mov_b64_e32 v[58:59], v[8:9]
	v_mov_b64_e32 v[56:57], v[6:7]
	v_mov_b64_e32 v[54:55], v[4:5]
	v_mov_b64_e32 v[52:53], v[2:3]
	v_mov_b64_e32 v[50:51], v[0:1]
	v_mov_b64_e32 v[46:47], v[12:13]
	v_mov_b64_e32 v[44:45], v[10:11]
	v_mov_b64_e32 v[42:43], v[8:9]
	v_mov_b64_e32 v[40:41], v[6:7]
	v_mov_b64_e32 v[38:39], v[4:5]
	v_mov_b64_e32 v[36:37], v[2:3]
	v_mov_b64_e32 v[34:35], v[0:1]
	v_mov_b64_e32 v[30:31], v[12:13]
	v_mov_b64_e32 v[28:29], v[10:11]
	v_mov_b64_e32 v[26:27], v[8:9]
	v_mov_b64_e32 v[24:25], v[6:7]
	v_mov_b64_e32 v[22:23], v[4:5]
	v_mov_b64_e32 v[20:21], v[2:3]
	v_mov_b64_e32 v[18:19], v[0:1]
	v_mov_b64_e32 v[16:17], v[14:15]
	v_mov_b64_e32 v[14:15], v[12:13]
	v_mov_b64_e32 v[12:13], v[10:11]
	v_mov_b64_e32 v[10:11], v[8:9]
	v_mov_b64_e32 v[8:9], v[6:7]
	v_mov_b64_e32 v[6:7], v[4:5]
	v_mov_b64_e32 v[4:5], v[2:3]
	v_mov_b64_e32 v[2:3], v[0:1]
	s_branch .LBB0_2342

.LBB0_2342:
	s_add_i32 s69, s68, -3
	s_cmp_lt_u32 s69, s56
	s_cselect_b64 s[38:39], -1, 0
	s_cmp_ge_u32 s69, s56
	s_waitcnt vmcnt(7)
	ds_write_b128 v227, v[148:151] offset:37888
	s_waitcnt vmcnt(6)
	ds_write_b128 v228, v[152:155] offset:37888
	s_waitcnt vmcnt(5)
	ds_write_b128 v232, v[156:159] offset:55296
	s_waitcnt vmcnt(4)
	ds_write_b128 v233, v[160:163] offset:55296
	s_cbranch_scc1 .LBB0_2344
	s_add_i32 s12, s36, 0xffffffa0
	s_lshl_b64 s[40:41], s[12:13], 9
	s_sub_i32 s12, s36, 64
	v_lshl_add_u64 v[68:69], v[190:191], 0, s[40:41]
	s_lshl_b64 s[70:71], s[12:13], 9
	v_lshl_add_u64 v[70:71], v[190:191], 0, s[70:71]
	global_load_dwordx4 v[148:151], v[68:69], off
	global_load_dwordx4 v[152:155], v[70:71], off
	v_lshl_add_u64 v[68:69], v[192:193], 0, s[40:41]
	v_lshl_add_u64 v[70:71], v[192:193], 0, s[70:71]
	global_load_dwordx4 v[156:159], v[68:69], off
	global_load_dwordx4 v[160:163], v[70:71], off
	s_add_u32 s100, s40, 0x10000
	s_addc_u32 s101, s41, 0
	v_lshl_add_u64 v[248:249], v[190:191], 0, s[100:101]
	global_load_dword v244, v[248:249], off
	v_lshl_add_u64 v[248:249], v[192:193], 0, s[100:101]
	global_load_dword v246, v[248:249], off
	s_add_u32 s100, s70, 0x10000
	s_addc_u32 s101, s71, 0
	v_lshl_add_u64 v[248:249], v[190:191], 0, s[100:101]
	global_load_dword v245, v[248:249], off
	v_lshl_add_u64 v[248:249], v[192:193], 0, s[100:101]
	global_load_dword v247, v[248:249], off

.LBB0_2412:
	v_sub_f32_e32 v0, v91, v66
	v_sub_f32_e32 v90, v90, v66
	v_sub_f32_e32 v89, v89, v66
	v_sub_f32_e32 v88, v88, v66
	v_sub_f32_e32 v87, v87, v66
	v_sub_f32_e32 v86, v86, v66
	v_sub_f32_e32 v85, v85, v66
	v_sub_f32_e32 v84, v84, v66
	v_exp_f32_e32 v196, v84
	v_exp_f32_e32 v197, v85
	v_exp_f32_e32 v200, v86
	v_exp_f32_e32 v201, v87
	v_exp_f32_e32 v198, v88
	v_exp_f32_e32 v199, v89
	v_exp_f32_e32 v194, v90
	v_exp_f32_e32 v195, v0
	v_cvt_pk_bf16_f32 v84, v196, v197
	v_cvt_pk_bf16_f32 v85, v200, v201
	v_cvt_pk_bf16_f32 v86, v198, v199
	v_cvt_pk_bf16_f32 v87, v194, v195
	v_sub_f32_e32 v0, v99, v66
	v_sub_f32_e32 v88, v98, v66
	s_waitcnt lgkmcnt(3)
	v_mfma_f32_32x32x16_bf16 v[50:65], v[176:179], v[84:87], v[50:65]
	v_sub_f32_e32 v89, v97, v66
	v_sub_f32_e32 v90, v96, v66
	v_sub_f32_e32 v91, v95, v66
	v_sub_f32_e32 v94, v94, v66
	v_sub_f32_e32 v93, v93, v66
	v_sub_f32_e32 v92, v92, v66
	v_exp_f32_e32 v206, v92
	s_waitcnt lgkmcnt(2)
	v_mfma_f32_32x32x16_bf16 v[34:49], v[172:175], v[84:87], v[34:49]
	v_exp_f32_e32 v207, v93
	v_exp_f32_e32 v208, v94
	v_exp_f32_e32 v209, v91
	v_exp_f32_e32 v202, v90
	v_exp_f32_e32 v203, v89
	v_exp_f32_e32 v204, v88
	v_exp_f32_e32 v205, v0
	s_waitcnt lgkmcnt(1)
	v_mfma_f32_32x32x16_bf16 v[18:33], v[168:171], v[84:87], v[18:33]
	ds_read_b64_tr_b16 v[92:93], v235 offset:22528
	ds_read_b64_tr_b16 v[94:95], v235 offset:25088
	v_cvt_pk_bf16_f32 v88, v206, v207
	v_cvt_pk_bf16_f32 v89, v208, v209
	v_cvt_pk_bf16_f32 v90, v202, v203
	v_cvt_pk_bf16_f32 v91, v204, v205
	v_sub_f32_e32 v0, v75, v66
	v_sub_f32_e32 v74, v74, v66
	s_waitcnt lgkmcnt(2)
	v_mfma_f32_32x32x16_bf16 v[2:17], v[164:167], v[84:87], v[2:17]
	ds_read_b64_tr_b16 v[84:85], v235 offset:22592
	ds_read_b64_tr_b16 v[96:97], v235 offset:22656
	ds_read_b64_tr_b16 v[100:101], v235 offset:22720
	ds_read_b64_tr_b16 v[86:87], v235 offset:25152
	ds_read_b64_tr_b16 v[98:99], v235 offset:25216
	ds_read_b64_tr_b16 v[102:103], v235 offset:25280
	v_sub_f32_e32 v73, v73, v66
	v_sub_f32_e32 v72, v72, v66
	v_sub_f32_e32 v71, v71, v66
	v_sub_f32_e32 v70, v70, v66
	v_sub_f32_e32 v69, v69, v66
	v_sub_f32_e32 v68, v68, v66
	s_waitcnt lgkmcnt(6)
	v_mfma_f32_32x32x16_bf16 v[50:65], v[92:95], v[88:91], v[50:65]
	v_exp_f32_e32 v214, v68
	v_exp_f32_e32 v215, v69
	v_exp_f32_e32 v216, v70
	v_exp_f32_e32 v217, v71
	v_exp_f32_e32 v212, v72
	v_exp_f32_e32 v213, v73
	v_exp_f32_e32 v210, v74
	s_waitcnt lgkmcnt(2)
	v_mfma_f32_32x32x16_bf16 v[34:49], v[84:87], v[88:91], v[34:49]
	v_exp_f32_e32 v211, v0
	ds_read_b64_tr_b16 v[72:73], v235 offset:27648
	ds_read_b64_tr_b16 v[74:75], v235 offset:30208
	v_cvt_pk_bf16_f32 v68, v214, v215
	v_cvt_pk_bf16_f32 v69, v216, v217
	v_cvt_pk_bf16_f32 v70, v212, v213
	v_cvt_pk_bf16_f32 v71, v210, v211
	v_sub_f32_e32 v0, v83, v66
	s_waitcnt lgkmcnt(3)
	v_mfma_f32_32x32x16_bf16 v[18:33], v[96:99], v[88:91], v[18:33]
	v_sub_f32_e32 v78, v78, v66
	v_sub_f32_e32 v77, v77, v66
	v_sub_f32_e32 v76, v76, v66
	v_exp_f32_e32 v222, v76
	v_exp_f32_e32 v223, v77
	v_exp_f32_e32 v224, v78
	v_exp_f32_e32 v219, v0
	s_waitcnt lgkmcnt(2)
	v_mfma_f32_32x32x16_bf16 v[2:17], v[100:103], v[88:91], v[2:17]
	ds_read_b64_tr_b16 v[84:85], v235 offset:27712
	ds_read_b64_tr_b16 v[88:89], v235 offset:27776
	ds_read_b64_tr_b16 v[92:93], v235 offset:27840
	ds_read_b64_tr_b16 v[86:87], v235 offset:30272
	ds_read_b64_tr_b16 v[90:91], v235 offset:30336
	ds_read_b64_tr_b16 v[94:95], v235 offset:30400
	s_andn2_b64 vcc, exec, s[38:39]
	s_waitcnt lgkmcnt(6)
	v_mfma_f32_32x32x16_bf16 v[50:65], v[72:75], v[68:71], v[50:65]
	v_sub_f32_e32 v72, v82, v66
	v_sub_f32_e32 v73, v81, v66
	v_sub_f32_e32 v74, v80, v66
	v_sub_f32_e32 v75, v79, v66
	v_exp_f32_e32 v225, v75
	v_exp_f32_e32 v220, v74
	v_exp_f32_e32 v221, v73
	s_waitcnt lgkmcnt(2)
	v_mfma_f32_32x32x16_bf16 v[34:49], v[84:87], v[68:71], v[34:49]
	v_exp_f32_e32 v218, v72
	ds_read_b64_tr_b16 v[76:77], v235 offset:32768
	ds_read_b64_tr_b16 v[78:79], v235 offset:35328
	v_cvt_pk_bf16_f32 v72, v222, v223
	v_cvt_pk_bf16_f32 v73, v224, v225
	v_cvt_pk_bf16_f32 v74, v220, v221
	v_cvt_pk_bf16_f32 v75, v218, v219
	s_waitcnt lgkmcnt(3)
	v_mfma_f32_32x32x16_bf16 v[18:33], v[88:91], v[68:71], v[18:33]
	s_waitcnt lgkmcnt(2)
	v_mfma_f32_32x32x16_bf16 v[2:17], v[92:95], v[68:71], v[2:17]
	ds_read_b64_tr_b16 v[68:69], v235 offset:32832
	ds_read_b64_tr_b16 v[80:81], v235 offset:32896
	ds_read_b64_tr_b16 v[84:85], v235 offset:32960
	ds_read_b64_tr_b16 v[70:71], v235 offset:35392
	ds_read_b64_tr_b16 v[82:83], v235 offset:35456
	ds_read_b64_tr_b16 v[86:87], v235 offset:35520
	s_waitcnt lgkmcnt(0)
	s_barrier
	s_waitcnt lgkmcnt(6)
	v_mfma_f32_32x32x16_bf16 v[50:65], v[76:79], v[72:75], v[50:65]
	s_waitcnt lgkmcnt(2)
	v_mfma_f32_32x32x16_bf16 v[34:49], v[68:71], v[72:75], v[34:49]
	s_waitcnt lgkmcnt(1)
	v_mfma_f32_32x32x16_bf16 v[18:33], v[80:83], v[72:75], v[18:33]
	s_waitcnt lgkmcnt(0)
	v_mfma_f32_32x32x16_bf16 v[2:17], v[84:87], v[72:75], v[2:17]
	s_cbranch_vccnz .LBB0_2414
	s_waitcnt vmcnt(7)
	ds_write_b128 v227, v[148:151]
	s_waitcnt vmcnt(6)
	ds_write_b128 v228, v[152:155]
	s_waitcnt vmcnt(5)
	ds_write_b128 v232, v[156:159] offset:17408
	s_waitcnt vmcnt(4)
	ds_write_b128 v233, v[160:163] offset:17408
.LBB0_2414:
	s_cmp_ge_u32 s68, s66
	s_cbranch_scc1 .LBB0_2416
	s_sub_i32 s12, s36, 32
	s_lshl_b64 s[38:39], s[12:13], 9
	s_mov_b32 s37, s13
	v_lshl_add_u64 v[68:69], v[190:191], 0, s[38:39]
	s_lshl_b64 s[40:41], s[36:37], 9
	v_lshl_add_u64 v[70:71], v[190:191], 0, s[40:41]
	global_load_dwordx4 v[148:151], v[68:69], off
	global_load_dwordx4 v[152:155], v[70:71], off
	v_lshl_add_u64 v[68:69], v[192:193], 0, s[38:39]
	v_lshl_add_u64 v[70:71], v[192:193], 0, s[40:41]
	global_load_dwordx4 v[156:159], v[68:69], off
	global_load_dwordx4 v[160:163], v[70:71], off
	s_add_u32 s100, s38, 0x10000
	s_addc_u32 s101, s39, 0
	v_lshl_add_u64 v[248:249], v[190:191], 0, s[100:101]
	global_load_dword v244, v[248:249], off
	v_lshl_add_u64 v[248:249], v[192:193], 0, s[100:101]
	global_load_dword v246, v[248:249], off
	s_add_u32 s100, s40, 0x10000
	s_addc_u32 s101, s41, 0
	v_lshl_add_u64 v[248:249], v[190:191], 0, s[100:101]
	global_load_dword v245, v[248:249], off
	v_lshl_add_u64 v[248:249], v[192:193], 0, s[100:101]
	global_load_dword v247, v[248:249], off

	.amdhsa_kernel _Z10hybrid_fwd4Args
		.amdhsa_group_segment_fixed_size 0
		.amdhsa_private_segment_fixed_size 0
		.amdhsa_kernarg_size 440
		.amdhsa_user_sgpr_count 2
		.amdhsa_user_sgpr_dispatch_ptr 0
		.amdhsa_user_sgpr_queue_ptr 0
		.amdhsa_user_sgpr_kernarg_segment_ptr 1
		.amdhsa_user_sgpr_dispatch_id 0
		.amdhsa_user_sgpr_kernarg_preload_length 0
		.amdhsa_user_sgpr_kernarg_preload_offset 0
		.amdhsa_user_sgpr_private_segment_size 0
		.amdhsa_uses_dynamic_stack 0
		.amdhsa_enable_private_segment 0
		.amdhsa_system_sgpr_workgroup_id_x 1
		.amdhsa_system_sgpr_workgroup_id_y 0
		.amdhsa_system_sgpr_workgroup_id_z 0
		.amdhsa_system_sgpr_workgroup_info 0
		.amdhsa_system_vgpr_workitem_id 0
		.amdhsa_next_free_vgpr 251
		.amdhsa_next_free_sgpr 102
		.amdhsa_accum_offset 252
		.amdhsa_reserve_vcc 1
		.amdhsa_float_round_mode_32 0
		.amdhsa_float_round_mode_16_64 0
		.amdhsa_float_denorm_mode_32 3
		.amdhsa_float_denorm_mode_16_64 3
		.amdhsa_dx10_clamp 1
		.amdhsa_ieee_mode 1
		.amdhsa_fp16_overflow 0
		.amdhsa_tg_split 0
		.amdhsa_exception_fp_ieee_invalid_op 0
		.amdhsa_exception_fp_denorm_src 0
		.amdhsa_exception_fp_ieee_div_zero 0
		.amdhsa_exception_fp_ieee_overflow 0
		.amdhsa_exception_fp_ieee_underflow 0
		.amdhsa_exception_fp_ieee_inexact 0
		.amdhsa_exception_int_div_zero 0
	.end_amdhsa_kernel

amdhsa.kernels:
  - .agpr_count:     0
    .args:
      - .offset:         0
        .size:           184
        .value_kind:     by_value
      - .offset:         184
        .size:           4
        .value_kind:     hidden_block_count_x
      - .offset:         188
        .size:           4
        .value_kind:     hidden_block_count_y
      - .offset:         192
        .size:           4
        .value_kind:     hidden_block_count_z
      - .offset:         196
        .size:           2
        .value_kind:     hidden_group_size_x
      - .offset:         198
        .size:           2
        .value_kind:     hidden_group_size_y
      - .offset:         200
        .size:           2
        .value_kind:     hidden_group_size_z
      - .offset:         202
        .size:           2
        .value_kind:     hidden_remainder_x
      - .offset:         204
        .size:           2
        .value_kind:     hidden_remainder_y
      - .offset:         206
        .size:           2
        .value_kind:     hidden_remainder_z
      - .offset:         224
        .size:           8
        .value_kind:     hidden_global_offset_x
      - .offset:         232
        .size:           8
        .value_kind:     hidden_global_offset_y
      - .offset:         240
        .size:           8
        .value_kind:     hidden_global_offset_z
      - .offset:         248
        .size:           2
        .value_kind:     hidden_grid_dims
      - .offset:         304
        .size:           4
        .value_kind:     hidden_dynamic_lds_size
    .group_segment_fixed_size: 0
    .kernarg_segment_align: 8
    .kernarg_segment_size: 440
    .language:       OpenCL C
    .language_version:
      - 2
      - 0
    .max_flat_workgroup_size: 512
    .name:           _Z10hybrid_fwd4Args
    .private_segment_fixed_size: 0
    .sgpr_count:     108
    .sgpr_spill_count: 34
    .symbol:         _Z10hybrid_fwd4Args.kd
    .uniform_work_group_size: 1
    .uses_dynamic_stack: false
    .vgpr_count:     251
    .vgpr_spill_count: 0
    .wavefront_size: 64
